# nt on the transposer stores issued during the mixers phases (keep proj/hyena data resident in cache)
# speedup vs baseline: 1.0181x; 1.0181x over previous
.Ltrm_after9:
	ds_write_b32 v1, v10 offset:0
	ds_write_b32 v1, v11 offset:4
	ds_write_b32 v1, v12 offset:8
	ds_write_b32 v1, v13 offset:12
	ds_write_b32 v1, v14 offset:1056
	ds_write_b32 v1, v15 offset:1060
	ds_write_b32 v1, v16 offset:1064
	ds_write_b32 v1, v17 offset:1068
	ds_write_b32 v1, v18 offset:2112
	ds_write_b32 v1, v19 offset:2116
	ds_write_b32 v1, v20 offset:2120
	ds_write_b32 v1, v21 offset:2124
	ds_write_b32 v1, v22 offset:3168
	ds_write_b32 v1, v23 offset:3172
	ds_write_b32 v1, v24 offset:3176
	ds_write_b32 v1, v25 offset:3180
	ds_write_b32 v1, v26 offset:4224
	ds_write_b32 v1, v27 offset:4228
	ds_write_b32 v1, v28 offset:4232
	ds_write_b32 v1, v29 offset:4236
	ds_write_b32 v1, v30 offset:5280
	ds_write_b32 v1, v31 offset:5284
	ds_write_b32 v1, v32 offset:5288
	ds_write_b32 v1, v33 offset:5292
	ds_write_b32 v1, v34 offset:6336
	ds_write_b32 v1, v35 offset:6340
	ds_write_b32 v1, v36 offset:6344
	ds_write_b32 v1, v37 offset:6348
	ds_write_b32 v1, v38 offset:7392
	ds_write_b32 v1, v39 offset:7396
	ds_write_b32 v1, v40 offset:7400
	ds_write_b32 v1, v41 offset:7404
	v_mad_u32_u24 v9, v5, s22, v6
	s_lshl_b32 s46, s22, 3
	s_waitcnt lgkmcnt(0)
	ds_read_b32 v74, v2 offset:0
	ds_read_b32 v75, v2 offset:132
	ds_read_b32 v76, v2 offset:264
	ds_read_b32 v77, v2 offset:396
	ds_read_b32 v78, v2 offset:528
	ds_read_b32 v79, v2 offset:660
	ds_read_b32 v80, v2 offset:792
	ds_read_b32 v81, v2 offset:924
	ds_read_b32 v82, v2 offset:32
	ds_read_b32 v83, v2 offset:164
	ds_read_b32 v84, v2 offset:296
	ds_read_b32 v85, v2 offset:428
	ds_read_b32 v86, v2 offset:560
	ds_read_b32 v87, v2 offset:692
	ds_read_b32 v88, v2 offset:824
	ds_read_b32 v89, v2 offset:956
	s_waitcnt lgkmcnt(8)
	v_cvt_pk_bf16_f32 v106, v74, v75
	v_cvt_pk_bf16_f32 v107, v76, v77
	v_cvt_pk_bf16_f32 v108, v78, v79
	v_cvt_pk_bf16_f32 v109, v80, v81
	global_store_dwordx4 v9, v[106:109], s[18:19] nt
	s_add_u32 s18, s18, s46
	s_addc_u32 s19, s19, 0
	ds_read_b32 v90, v2 offset:64
	ds_read_b32 v91, v2 offset:196
	ds_read_b32 v92, v2 offset:328
	ds_read_b32 v93, v2 offset:460
	ds_read_b32 v94, v2 offset:592
	ds_read_b32 v95, v2 offset:724
	ds_read_b32 v96, v2 offset:856
	ds_read_b32 v97, v2 offset:988
	s_waitcnt lgkmcnt(8)
	v_cvt_pk_bf16_f32 v110, v82, v83
	v_cvt_pk_bf16_f32 v111, v84, v85
	v_cvt_pk_bf16_f32 v112, v86, v87
	v_cvt_pk_bf16_f32 v113, v88, v89
	global_store_dwordx4 v9, v[110:113], s[18:19] nt
	s_add_u32 s18, s18, s46
	s_addc_u32 s19, s19, 0
	ds_read_b32 v98, v2 offset:96
	ds_read_b32 v99, v2 offset:228
	ds_read_b32 v100, v2 offset:360
	ds_read_b32 v101, v2 offset:492
	ds_read_b32 v102, v2 offset:624
	ds_read_b32 v103, v2 offset:756
	ds_read_b32 v104, v2 offset:888
	ds_read_b32 v105, v2 offset:1020
	s_waitcnt lgkmcnt(8)
	v_cvt_pk_bf16_f32 v106, v90, v91
	v_cvt_pk_bf16_f32 v107, v92, v93
	v_cvt_pk_bf16_f32 v108, v94, v95
	v_cvt_pk_bf16_f32 v109, v96, v97
	global_store_dwordx4 v9, v[106:109], s[18:19] nt
	s_add_u32 s18, s18, s46
	s_addc_u32 s19, s19, 0
	s_waitcnt lgkmcnt(0)
	v_cvt_pk_bf16_f32 v110, v98, v99
	v_cvt_pk_bf16_f32 v111, v100, v101
	v_cvt_pk_bf16_f32 v112, v102, v103
	v_cvt_pk_bf16_f32 v113, v104, v105
	global_store_dwordx4 v9, v[110:113], s[18:19] nt
	s_cmp_eq_u32 s24, 0
	s_cbranch_scc1 .Ltrm_done
	s_add_u32 s12, s12, 1024
	s_cmp_lt_u32 s12, 33280
	s_cselect_b32 s24, 1, 0
	s_cbranch_scc0 .Ltrm_nonext17
	s_cmp_ge_u32 s12, 33280
	s_cselect_b32 s41, 1, 0
	s_cselect_b32 s26, 33280, 0
	s_sub_u32 s42, s12, s26
	s_cmp_ge_u32 s42, 12288
	s_cbranch_scc1 .Ltrm_m20
	s_mul_i32 s43, s42, 43691
	s_lshr_b32 s43, s43, 24
	s_mul_i32 s26, s43, 384
	s_sub_u32 s44, s42, s26
	s_mov_b32 s14, s0
	s_mov_b32 s15, s1
	s_mov_b32 s36, 0xc000
	s_mov_b32 s37, 0x6000000
	s_mov_b32 s38, 0x0
	s_mov_b32 s39, 0x3000000
	s_mov_b32 s40, 0x1000
	s_branch .Ltrm_dec_done19
